# up epilogue H stores with cache policy 'sc0 nt' (policy sweep), on top of v59
# baseline (speedup 1.0000x reference)
; __device__ __forceinline__ unsigned cvt_pk_bf16(float lo, float hi) { unsigned r; asm volatile("v_cvt_pk_bf16_f32 %0, %1, %2" : "=v"(r) : "v"(lo), "v"(hi)); return r; }
;     __device__ __forceinline__ void operator()(const f32x4 (&acc)[2][2][4][2], const Unit& u, int ui, int wr, int wc, int fr, int fq) const {
;     ...
;             for (int m = 0; m < 4; ++m) rs[ai][m] = row_rstd(lds, ui, ai * HALF + wr * 64 + m * 16 + fr);
; #pragma unroll
;         for (int ai = 0; ai < 2; ++ai)
; #pragma unroll
;             for (int m = 0; m < 4; ++m) { const float r = rs[ai][m]; const int row = row0 + ai * HALF + m * 16;
;                 const float c1 = r * -1.44269504089f, r2 = r * r; u32x4 w;
; #pragma unroll
;                 for (int n = 0; n < 2; ++n)
; #pragma unroll
;                     for (int p = 0; p < 2; ++p) { const f32x2 g = (f32x2){acc[ai][0][m][n][2 * p], acc[ai][0][m][n][2 * p + 1]}, uu = (f32x2){acc[ai][1][m][n][2 * p], acc[ai][1][m][n][2 * p + 1]};
;                         const f32x2 t = g * c1; f32x2 d; d.x = __builtin_amdgcn_exp2f(t.x); d.y = __builtin_amdgcn_exp2f(t.y); d = d + 1.0f;
;                         f32x2 q; q.x = __builtin_amdgcn_rcpf(d.x); q.y = __builtin_amdgcn_rcpf(d.y);
;                         const f32x2 hh = (g * uu) * (q * r2); w[2 * n + p] = cvt_pk_bf16(hh.x, hh.y); }
;                 __builtin_nontemporal_store(w, (u32x4*)(H + (size_t)row * ldh + col0)); }
.LBB0_449:
	v_mov_b32_e32 v140, v147
	v_mov_b32_e32 v167, v164
	v_pk_mul_f32 v[120:121], v[124:125], v[120:121]
	v_add_u32_e32 v171, s35, v140
	v_lshlrev_b32_e32 v140, 2, v171
	v_lshl_add_u32 v140, s48, 10, v140
	v_add_u32_e32 v140, 0x20400, v140
	ds_read2_b32 v[168:169], v140 offset1:16
	ds_read2_b32 v[162:163], v140 offset0:32 offset1:48
	ds_read2_b32 v[142:143], v140 offset0:128 offset1:144
	ds_read2_b32 v[140:141], v140 offset0:160 offset1:176
	v_pk_mul_f32 v[122:123], v[126:127], v[122:123]
	s_waitcnt lgkmcnt(0)
	v_mul_f32_e32 v172, 0xbfb8aa3b, v168
	v_pk_mul_f32 v[174:175], v[124:125], v[172:173] op_sel_hi:[1,0]
	v_pk_mul_f32 v[124:125], v[126:127], v[172:173] op_sel_hi:[1,0]
	v_exp_f32_e32 v174, v174
	v_exp_f32_e32 v175, v175
	v_exp_f32_e32 v124, v124
	v_exp_f32_e32 v125, v125
	v_mul_f32_e32 v168, v168, v168
	v_pk_add_f32 v[174:175], v[174:175], 1.0 op_sel_hi:[1,0]
	v_pk_mul_f32 v[112:113], v[116:117], v[112:113]
	v_rcp_f32_e32 v174, v174
	v_rcp_f32_e32 v175, v175
	v_pk_add_f32 v[124:125], v[124:125], 1.0 op_sel_hi:[1,0]
	v_pk_mul_f32 v[114:115], v[118:119], v[114:115]
	v_rcp_f32_e32 v124, v124
	v_rcp_f32_e32 v125, v125
	v_pk_mul_f32 v[126:127], v[168:169], v[174:175] op_sel_hi:[0,1]
	v_pk_mul_f32 v[120:121], v[120:121], v[126:127]
	v_pk_mul_f32 v[126:127], v[116:117], v[172:173] op_sel_hi:[1,0]
	v_pk_mul_f32 v[124:125], v[168:169], v[124:125] op_sel_hi:[0,1]
	v_exp_f32_e32 v126, v126
	v_exp_f32_e32 v127, v127
	v_pk_mul_f32 v[122:123], v[122:123], v[124:125]
	v_pk_mul_f32 v[124:125], v[118:119], v[172:173] op_sel_hi:[1,0]
	v_cvt_pk_bf16_f32 v120, v120, v121
	v_cvt_pk_bf16_f32 v121, v122, v123
	v_pk_add_f32 v[122:123], v[126:127], 1.0 op_sel_hi:[1,0]
	v_exp_f32_e32 v124, v124
	v_exp_f32_e32 v125, v125
	v_rcp_f32_e32 v122, v122
	v_rcp_f32_e32 v123, v123
	s_lshl_b32 s5, s47, 7
	v_pk_add_f32 v[116:117], v[124:125], 1.0 op_sel_hi:[1,0]
	s_or_b32 s5, s5, s36
	v_rcp_f32_e32 v116, v116
	v_rcp_f32_e32 v117, v117
	v_pk_mul_f32 v[118:119], v[168:169], v[122:123] op_sel_hi:[0,1]
	v_pk_mul_f32 v[112:113], v[112:113], v[118:119]
	v_mul_f32_e32 v118, 0xbfb8aa3b, v169
	v_cvt_pk_bf16_f32 v122, v112, v113
	v_pk_mul_f32 v[112:113], v[168:169], v[116:117] op_sel_hi:[0,1]
	v_pk_mul_f32 v[124:125], v[108:109], v[118:119] op_sel_hi:[1,0]
	v_lshl_add_u32 v170, v167, 3, s5
	v_pk_mul_f32 v[112:113], v[114:115], v[112:113]
	v_exp_f32_e32 v124, v124
	v_exp_f32_e32 v125, v125
	v_lshl_add_u32 v167, s46, 8, v171
	v_ashrrev_i32_e32 v171, 31, v170
	v_cvt_pk_bf16_f32 v123, v112, v113
	v_mov_b64_e32 v[112:113], s[20:21]
	v_pk_mul_f32 v[104:105], v[108:109], v[104:105]
	v_pk_mul_f32 v[108:109], v[110:111], v[118:119] op_sel_hi:[1,0]
	v_mad_i64_i32 v[116:117], s[14:15], v167, s59, v[112:113]
	v_lshlrev_b64 v[114:115], 1, v[170:171]
	v_exp_f32_e32 v108, v108
	v_exp_f32_e32 v109, v109
	v_lshl_add_u64 v[116:117], v[116:117], 0, v[114:115]
	global_store_dwordx4 v[116:117], v[120:123], off sc0 nt
	v_mul_f32_e32 v116, v169, v169
	v_pk_add_f32 v[108:109], v[108:109], 1.0 op_sel_hi:[1,0]
	v_pk_add_f32 v[120:121], v[124:125], 1.0 op_sel_hi:[1,0]
	v_rcp_f32_e32 v108, v108
	v_rcp_f32_e32 v120, v120
	v_rcp_f32_e32 v121, v121
	v_rcp_f32_e32 v109, v109
	v_pk_mul_f32 v[106:107], v[110:111], v[106:107]
	v_pk_mul_f32 v[96:97], v[100:101], v[96:97]
	v_pk_mul_f32 v[110:111], v[116:117], v[120:121] op_sel_hi:[0,1]
	v_pk_mul_f32 v[104:105], v[104:105], v[110:111]
	v_pk_mul_f32 v[110:111], v[100:101], v[118:119] op_sel_hi:[1,0]
	v_pk_mul_f32 v[108:109], v[116:117], v[108:109] op_sel_hi:[0,1]
	v_exp_f32_e32 v110, v110
	v_exp_f32_e32 v111, v111
	v_pk_mul_f32 v[106:107], v[106:107], v[108:109]
	v_pk_mul_f32 v[108:109], v[102:103], v[118:119] op_sel_hi:[1,0]
	v_cvt_pk_bf16_f32 v104, v104, v105
	v_cvt_pk_bf16_f32 v105, v106, v107
	v_pk_add_f32 v[106:107], v[110:111], 1.0 op_sel_hi:[1,0]
	v_exp_f32_e32 v108, v108
	v_exp_f32_e32 v109, v109
	v_rcp_f32_e32 v106, v106
	v_rcp_f32_e32 v107, v107
	v_pk_mul_f32 v[98:99], v[102:103], v[98:99]
	v_pk_add_f32 v[100:101], v[108:109], 1.0 op_sel_hi:[1,0]
	v_pk_mul_f32 v[88:89], v[92:93], v[88:89]
	v_rcp_f32_e32 v100, v100
	v_rcp_f32_e32 v101, v101
	v_pk_mul_f32 v[102:103], v[116:117], v[106:107] op_sel_hi:[0,1]
	v_pk_mul_f32 v[96:97], v[96:97], v[102:103]
	v_pk_mul_f32 v[90:91], v[94:95], v[90:91]
	v_cvt_pk_bf16_f32 v106, v96, v97
	v_pk_mul_f32 v[96:97], v[116:117], v[100:101] op_sel_hi:[0,1]
	v_pk_mul_f32 v[96:97], v[98:99], v[96:97]
	v_mul_f32_e32 v98, 0xbfb8aa3b, v162
	v_pk_mul_f32 v[100:101], v[92:93], v[98:99] op_sel_hi:[1,0]
	v_pk_mul_f32 v[92:93], v[94:95], v[98:99] op_sel_hi:[1,0]
	v_exp_f32_e32 v100, v100
	v_exp_f32_e32 v101, v101
	v_exp_f32_e32 v92, v92
	v_exp_f32_e32 v93, v93
	v_cvt_pk_bf16_f32 v107, v96, v97
	v_pk_add_f32 v[100:101], v[100:101], 1.0 op_sel_hi:[1,0]
	v_add_u32_e32 v96, 16, v167
	v_rcp_f32_e32 v100, v100
	v_rcp_f32_e32 v101, v101
	v_mad_i64_i32 v[96:97], s[14:15], v96, s59, v[112:113]
	v_pk_add_f32 v[92:93], v[92:93], 1.0 op_sel_hi:[1,0]
	v_lshl_add_u64 v[96:97], v[96:97], 0, v[114:115]
	v_rcp_f32_e32 v92, v92
	v_rcp_f32_e32 v93, v93
	global_store_dwordx4 v[96:97], v[104:107], off sc0 nt
	v_mul_f32_e32 v96, v162, v162
	v_pk_mul_f32 v[94:95], v[96:97], v[100:101] op_sel_hi:[0,1]
	v_pk_mul_f32 v[88:89], v[88:89], v[94:95]
	v_pk_mul_f32 v[94:95], v[84:85], v[98:99] op_sel_hi:[1,0]
	v_pk_mul_f32 v[92:93], v[96:97], v[92:93] op_sel_hi:[0,1]
	v_exp_f32_e32 v94, v94
	v_exp_f32_e32 v95, v95
	v_pk_mul_f32 v[90:91], v[90:91], v[92:93]
	v_pk_mul_f32 v[92:93], v[86:87], v[98:99] op_sel_hi:[1,0]
	v_cvt_pk_bf16_f32 v88, v88, v89
	v_cvt_pk_bf16_f32 v89, v90, v91
	v_pk_add_f32 v[90:91], v[94:95], 1.0 op_sel_hi:[1,0]
	v_exp_f32_e32 v92, v92
; __device__ __forceinline__ unsigned cvt_pk_bf16(float lo, float hi) { unsigned r; asm volatile("v_cvt_pk_bf16_f32 %0, %1, %2" : "=v"(r) : "v"(lo), "v"(hi)); return r; }
;     __device__ __forceinline__ void operator()(const f32x4 (&acc)[2][2][4][2], const Unit& u, int ui, int wr, int wc, int fr, int fq) const {
;     ...
;             for (int m = 0; m < 4; ++m) { const float r = rs[ai][m]; const int row = row0 + ai * HALF + m * 16;
;                 const float c1 = r * -1.44269504089f, r2 = r * r; u32x4 w;
; #pragma unroll
;                 for (int n = 0; n < 2; ++n)
; #pragma unroll
;                     for (int p = 0; p < 2; ++p) { const f32x2 g = (f32x2){acc[ai][0][m][n][2 * p], acc[ai][0][m][n][2 * p + 1]}, uu = (f32x2){acc[ai][1][m][n][2 * p], acc[ai][1][m][n][2 * p + 1]};
;                         const f32x2 t = g * c1; f32x2 d; d.x = __builtin_amdgcn_exp2f(t.x); d.y = __builtin_amdgcn_exp2f(t.y); d = d + 1.0f;
;                         f32x2 q; q.x = __builtin_amdgcn_rcpf(d.x); q.y = __builtin_amdgcn_rcpf(d.y);
;                         const f32x2 hh = (g * uu) * (q * r2); w[2 * n + p] = cvt_pk_bf16(hh.x, hh.y); }
;                 __builtin_nontemporal_store(w, (u32x4*)(H + (size_t)row * ldh + col0)); }
	v_exp_f32_e32 v93, v93
	v_rcp_f32_e32 v90, v90
	v_rcp_f32_e32 v91, v91
	v_pk_mul_f32 v[80:81], v[84:85], v[80:81]
	v_pk_add_f32 v[84:85], v[92:93], 1.0 op_sel_hi:[1,0]
	v_pk_mul_f32 v[82:83], v[86:87], v[82:83]
	v_rcp_f32_e32 v84, v84
	v_rcp_f32_e32 v85, v85
	v_pk_mul_f32 v[86:87], v[96:97], v[90:91] op_sel_hi:[0,1]
	v_pk_mul_f32 v[80:81], v[80:81], v[86:87]
	v_pk_mul_f32 v[72:73], v[76:77], v[72:73]
	v_cvt_pk_bf16_f32 v90, v80, v81
	v_pk_mul_f32 v[80:81], v[96:97], v[84:85] op_sel_hi:[0,1]
	v_pk_mul_f32 v[80:81], v[82:83], v[80:81]
	v_mul_f32_e32 v82, 0xbfb8aa3b, v163
	v_pk_mul_f32 v[84:85], v[76:77], v[82:83] op_sel_hi:[1,0]
	v_pk_mul_f32 v[76:77], v[78:79], v[82:83] op_sel_hi:[1,0]
	v_exp_f32_e32 v84, v84
	v_exp_f32_e32 v85, v85
	v_exp_f32_e32 v76, v76
	v_exp_f32_e32 v77, v77
	v_cvt_pk_bf16_f32 v91, v80, v81
	v_pk_add_f32 v[84:85], v[84:85], 1.0 op_sel_hi:[1,0]
	v_add_u32_e32 v80, 32, v167
	v_rcp_f32_e32 v84, v84
	v_rcp_f32_e32 v85, v85
	v_mad_i64_i32 v[80:81], s[14:15], v80, s59, v[112:113]
	v_pk_add_f32 v[76:77], v[76:77], 1.0 op_sel_hi:[1,0]
	v_lshl_add_u64 v[80:81], v[80:81], 0, v[114:115]
	v_rcp_f32_e32 v76, v76
	v_rcp_f32_e32 v77, v77
	global_store_dwordx4 v[80:81], v[88:91], off sc0 nt
	v_mul_f32_e32 v80, v163, v163
	v_pk_mul_f32 v[74:75], v[78:79], v[74:75]
	v_pk_mul_f32 v[78:79], v[80:81], v[84:85] op_sel_hi:[0,1]
	v_pk_mul_f32 v[72:73], v[72:73], v[78:79]
	v_pk_mul_f32 v[78:79], v[68:69], v[82:83] op_sel_hi:[1,0]
	v_pk_mul_f32 v[76:77], v[80:81], v[76:77] op_sel_hi:[0,1]
	v_exp_f32_e32 v78, v78
	v_exp_f32_e32 v79, v79
	v_pk_mul_f32 v[74:75], v[74:75], v[76:77]
	v_pk_mul_f32 v[76:77], v[70:71], v[82:83] op_sel_hi:[1,0]
	v_cvt_pk_bf16_f32 v72, v72, v73
	v_cvt_pk_bf16_f32 v73, v74, v75
	v_pk_add_f32 v[74:75], v[78:79], 1.0 op_sel_hi:[1,0]
	v_exp_f32_e32 v76, v76
	v_exp_f32_e32 v77, v77
	v_rcp_f32_e32 v74, v74
	v_rcp_f32_e32 v75, v75
	v_pk_mul_f32 v[64:65], v[68:69], v[64:65]
	v_pk_add_f32 v[68:69], v[76:77], 1.0 op_sel_hi:[1,0]
	v_pk_mul_f32 v[66:67], v[70:71], v[66:67]
	v_rcp_f32_e32 v68, v68
	v_rcp_f32_e32 v69, v69
	v_pk_mul_f32 v[70:71], v[80:81], v[74:75] op_sel_hi:[0,1]
	v_pk_mul_f32 v[64:65], v[64:65], v[70:71]
	v_pk_mul_f32 v[56:57], v[60:61], v[56:57]
	v_cvt_pk_bf16_f32 v74, v64, v65
	v_pk_mul_f32 v[64:65], v[80:81], v[68:69] op_sel_hi:[0,1]
	v_pk_mul_f32 v[64:65], v[66:67], v[64:65]
	v_mul_f32_e32 v66, 0xbfb8aa3b, v142
	v_pk_mul_f32 v[68:69], v[60:61], v[66:67] op_sel_hi:[1,0]
	v_pk_mul_f32 v[60:61], v[62:63], v[66:67] op_sel_hi:[1,0]
	v_exp_f32_e32 v68, v68
	v_exp_f32_e32 v69, v69
	v_exp_f32_e32 v60, v60
	v_exp_f32_e32 v61, v61
	v_cvt_pk_bf16_f32 v75, v64, v65
	v_pk_add_f32 v[68:69], v[68:69], 1.0 op_sel_hi:[1,0]
	v_add_u32_e32 v64, 48, v167
	v_rcp_f32_e32 v68, v68
	v_rcp_f32_e32 v69, v69
	v_mad_i64_i32 v[64:65], s[14:15], v64, s59, v[112:113]
	v_pk_add_f32 v[60:61], v[60:61], 1.0 op_sel_hi:[1,0]
	v_lshl_add_u64 v[64:65], v[64:65], 0, v[114:115]
	v_rcp_f32_e32 v60, v60
	v_rcp_f32_e32 v61, v61
	global_store_dwordx4 v[64:65], v[72:75], off sc0 nt
	v_add_u32_e32 v65, 0x80, v167
	v_mul_f32_e32 v64, v142, v142
	v_pk_mul_f32 v[58:59], v[62:63], v[58:59]
	v_pk_mul_f32 v[62:63], v[64:65], v[68:69] op_sel_hi:[0,1]
	v_pk_mul_f32 v[56:57], v[56:57], v[62:63]
	v_pk_mul_f32 v[62:63], v[52:53], v[66:67] op_sel_hi:[1,0]
	v_pk_mul_f32 v[60:61], v[64:65], v[60:61] op_sel_hi:[0,1]
	v_exp_f32_e32 v62, v62
	v_exp_f32_e32 v63, v63
	v_pk_mul_f32 v[58:59], v[58:59], v[60:61]
	v_pk_mul_f32 v[60:61], v[54:55], v[66:67] op_sel_hi:[1,0]
	v_cvt_pk_bf16_f32 v56, v56, v57
	v_cvt_pk_bf16_f32 v57, v58, v59
	v_pk_add_f32 v[58:59], v[62:63], 1.0 op_sel_hi:[1,0]
	v_exp_f32_e32 v60, v60
	v_exp_f32_e32 v61, v61
	v_rcp_f32_e32 v58, v58
	v_rcp_f32_e32 v59, v59
	v_pk_mul_f32 v[48:49], v[52:53], v[48:49]
	v_pk_add_f32 v[52:53], v[60:61], 1.0 op_sel_hi:[1,0]
	v_pk_mul_f32 v[50:51], v[54:55], v[50:51]
	v_rcp_f32_e32 v52, v52
	v_rcp_f32_e32 v53, v53
	v_pk_mul_f32 v[54:55], v[64:65], v[58:59] op_sel_hi:[0,1]
	v_pk_mul_f32 v[48:49], v[48:49], v[54:55]
	v_pk_mul_f32 v[40:41], v[44:45], v[40:41]
	v_cvt_pk_bf16_f32 v58, v48, v49
	v_pk_mul_f32 v[48:49], v[64:65], v[52:53] op_sel_hi:[0,1]
	v_pk_mul_f32 v[48:49], v[50:51], v[48:49]
	v_mul_f32_e32 v50, 0xbfb8aa3b, v143
	v_pk_mul_f32 v[52:53], v[44:45], v[50:51] op_sel_hi:[1,0]
	v_pk_mul_f32 v[44:45], v[46:47], v[50:51] op_sel_hi:[1,0]
	v_exp_f32_e32 v52, v52
	v_exp_f32_e32 v53, v53
	v_exp_f32_e32 v44, v44
	v_exp_f32_e32 v45, v45
	v_cvt_pk_bf16_f32 v59, v48, v49
	v_pk_add_f32 v[52:53], v[52:53], 1.0 op_sel_hi:[1,0]
	v_mad_i64_i32 v[48:49], s[14:15], v65, s59, v[112:113]
	v_rcp_f32_e32 v52, v52
	v_rcp_f32_e32 v53, v53
	v_pk_add_f32 v[44:45], v[44:45], 1.0 op_sel_hi:[1,0]
	v_lshl_add_u64 v[48:49], v[48:49], 0, v[114:115]
	v_rcp_f32_e32 v44, v44
	v_rcp_f32_e32 v45, v45
	global_store_dwordx4 v[48:49], v[56:59], off sc0 nt
	v_mul_f32_e32 v48, v143, v143
	v_pk_mul_f32 v[42:43], v[46:47], v[42:43]
; __device__ __forceinline__ unsigned cvt_pk_bf16(float lo, float hi) { unsigned r; asm volatile("v_cvt_pk_bf16_f32 %0, %1, %2" : "=v"(r) : "v"(lo), "v"(hi)); return r; }
;     __device__ __forceinline__ void operator()(const f32x4 (&acc)[2][2][4][2], const Unit& u, int ui, int wr, int wc, int fr, int fq) const {
;     ...
;             for (int m = 0; m < 4; ++m) { const float r = rs[ai][m]; const int row = row0 + ai * HALF + m * 16;
;                 const float c1 = r * -1.44269504089f, r2 = r * r; u32x4 w;
; #pragma unroll
;                 for (int n = 0; n < 2; ++n)
; #pragma unroll
;                     for (int p = 0; p < 2; ++p) { const f32x2 g = (f32x2){acc[ai][0][m][n][2 * p], acc[ai][0][m][n][2 * p + 1]}, uu = (f32x2){acc[ai][1][m][n][2 * p], acc[ai][1][m][n][2 * p + 1]};
;                         const f32x2 t = g * c1; f32x2 d; d.x = __builtin_amdgcn_exp2f(t.x); d.y = __builtin_amdgcn_exp2f(t.y); d = d + 1.0f;
;                         f32x2 q; q.x = __builtin_amdgcn_rcpf(d.x); q.y = __builtin_amdgcn_rcpf(d.y);
;                         const f32x2 hh = (g * uu) * (q * r2); w[2 * n + p] = cvt_pk_bf16(hh.x, hh.y); }
;                 __builtin_nontemporal_store(w, (u32x4*)(H + (size_t)row * ldh + col0)); }
	v_pk_mul_f32 v[46:47], v[48:49], v[52:53] op_sel_hi:[0,1]
	v_pk_mul_f32 v[40:41], v[40:41], v[46:47]
	v_pk_mul_f32 v[46:47], v[36:37], v[50:51] op_sel_hi:[1,0]
	v_pk_mul_f32 v[44:45], v[48:49], v[44:45] op_sel_hi:[0,1]
	v_exp_f32_e32 v46, v46
	v_exp_f32_e32 v47, v47
	v_pk_mul_f32 v[42:43], v[42:43], v[44:45]
	v_pk_mul_f32 v[44:45], v[38:39], v[50:51] op_sel_hi:[1,0]
	v_cvt_pk_bf16_f32 v40, v40, v41
	v_cvt_pk_bf16_f32 v41, v42, v43
	v_pk_add_f32 v[42:43], v[46:47], 1.0 op_sel_hi:[1,0]
	v_exp_f32_e32 v44, v44
	v_exp_f32_e32 v45, v45
	v_rcp_f32_e32 v42, v42
	v_rcp_f32_e32 v43, v43
	v_pk_mul_f32 v[32:33], v[36:37], v[32:33]
	v_pk_add_f32 v[36:37], v[44:45], 1.0 op_sel_hi:[1,0]
	v_pk_mul_f32 v[34:35], v[38:39], v[34:35]
	v_rcp_f32_e32 v36, v36
	v_rcp_f32_e32 v37, v37
	v_pk_mul_f32 v[38:39], v[48:49], v[42:43] op_sel_hi:[0,1]
	v_pk_mul_f32 v[32:33], v[32:33], v[38:39]
	v_pk_mul_f32 v[24:25], v[28:29], v[24:25]
	v_cvt_pk_bf16_f32 v42, v32, v33
	v_pk_mul_f32 v[32:33], v[48:49], v[36:37] op_sel_hi:[0,1]
	v_pk_mul_f32 v[32:33], v[34:35], v[32:33]
	v_mul_f32_e32 v34, 0xbfb8aa3b, v140
	v_pk_mul_f32 v[36:37], v[28:29], v[34:35] op_sel_hi:[1,0]
	v_pk_mul_f32 v[28:29], v[30:31], v[34:35] op_sel_hi:[1,0]
	v_exp_f32_e32 v36, v36
	v_exp_f32_e32 v37, v37
	v_exp_f32_e32 v28, v28
	v_exp_f32_e32 v29, v29
	v_cvt_pk_bf16_f32 v43, v32, v33
	v_pk_add_f32 v[36:37], v[36:37], 1.0 op_sel_hi:[1,0]
	v_add_u32_e32 v32, 0x90, v167
	v_rcp_f32_e32 v36, v36
	v_rcp_f32_e32 v37, v37
	v_mad_i64_i32 v[32:33], s[14:15], v32, s59, v[112:113]
	v_pk_add_f32 v[28:29], v[28:29], 1.0 op_sel_hi:[1,0]
	v_lshl_add_u64 v[32:33], v[32:33], 0, v[114:115]
	v_rcp_f32_e32 v28, v28
	v_rcp_f32_e32 v29, v29
	global_store_dwordx4 v[32:33], v[40:43], off sc0 nt
	v_mul_f32_e32 v32, v140, v140
	v_pk_mul_f32 v[26:27], v[30:31], v[26:27]
	v_pk_mul_f32 v[30:31], v[32:33], v[36:37] op_sel_hi:[0,1]
	v_pk_mul_f32 v[24:25], v[24:25], v[30:31]
	v_pk_mul_f32 v[30:31], v[20:21], v[34:35] op_sel_hi:[1,0]
	v_pk_mul_f32 v[28:29], v[32:33], v[28:29] op_sel_hi:[0,1]
	v_exp_f32_e32 v30, v30
	v_exp_f32_e32 v31, v31
	v_pk_mul_f32 v[26:27], v[26:27], v[28:29]
	v_pk_mul_f32 v[28:29], v[22:23], v[34:35] op_sel_hi:[1,0]
	v_cvt_pk_bf16_f32 v24, v24, v25
	v_cvt_pk_bf16_f32 v25, v26, v27
	v_pk_add_f32 v[26:27], v[30:31], 1.0 op_sel_hi:[1,0]
	v_exp_f32_e32 v28, v28
	v_exp_f32_e32 v29, v29
	v_rcp_f32_e32 v26, v26
	v_rcp_f32_e32 v27, v27
	v_pk_mul_f32 v[16:17], v[20:21], v[16:17]
	v_pk_add_f32 v[20:21], v[28:29], 1.0 op_sel_hi:[1,0]
	v_pk_mul_f32 v[18:19], v[22:23], v[18:19]
	v_rcp_f32_e32 v20, v20
	v_rcp_f32_e32 v21, v21
	v_pk_mul_f32 v[22:23], v[32:33], v[26:27] op_sel_hi:[0,1]
	v_pk_mul_f32 v[16:17], v[16:17], v[22:23]
	v_pk_mul_f32 v[8:9], v[12:13], v[8:9]
	v_cvt_pk_bf16_f32 v26, v16, v17
	v_pk_mul_f32 v[16:17], v[32:33], v[20:21] op_sel_hi:[0,1]
	v_pk_mul_f32 v[16:17], v[18:19], v[16:17]
	v_mul_f32_e32 v18, 0xbfb8aa3b, v141
	v_pk_mul_f32 v[20:21], v[12:13], v[18:19] op_sel_hi:[1,0]
	v_pk_mul_f32 v[12:13], v[14:15], v[18:19] op_sel_hi:[1,0]
	v_exp_f32_e32 v20, v20
	v_exp_f32_e32 v21, v21
	v_exp_f32_e32 v12, v12
	v_exp_f32_e32 v13, v13
	v_cvt_pk_bf16_f32 v27, v16, v17
	v_pk_add_f32 v[20:21], v[20:21], 1.0 op_sel_hi:[1,0]
	v_add_u32_e32 v16, 0xa0, v167
	v_rcp_f32_e32 v20, v20
	v_rcp_f32_e32 v21, v21
	v_mad_i64_i32 v[16:17], s[14:15], v16, s59, v[112:113]
	v_pk_add_f32 v[12:13], v[12:13], 1.0 op_sel_hi:[1,0]
	v_lshl_add_u64 v[16:17], v[16:17], 0, v[114:115]
	v_rcp_f32_e32 v12, v12
	v_rcp_f32_e32 v13, v13
	global_store_dwordx4 v[16:17], v[24:27], off sc0 nt
	v_mul_f32_e32 v16, v141, v141
	v_pk_mul_f32 v[10:11], v[14:15], v[10:11]
	v_pk_mul_f32 v[14:15], v[16:17], v[20:21] op_sel_hi:[0,1]
	v_pk_mul_f32 v[8:9], v[8:9], v[14:15]
	v_pk_mul_f32 v[14:15], v[4:5], v[18:19] op_sel_hi:[1,0]
	v_pk_mul_f32 v[12:13], v[16:17], v[12:13] op_sel_hi:[0,1]
	v_exp_f32_e32 v14, v14
	v_exp_f32_e32 v15, v15
	v_pk_mul_f32 v[10:11], v[10:11], v[12:13]
	v_pk_mul_f32 v[12:13], v[6:7], v[18:19] op_sel_hi:[1,0]
	v_cvt_pk_bf16_f32 v8, v8, v9
	v_cvt_pk_bf16_f32 v9, v10, v11
	v_pk_add_f32 v[10:11], v[14:15], 1.0 op_sel_hi:[1,0]
	v_exp_f32_e32 v12, v12
	v_exp_f32_e32 v13, v13
	v_rcp_f32_e32 v10, v10
	v_rcp_f32_e32 v11, v11
	v_pk_mul_f32 v[0:1], v[4:5], v[0:1]
	v_pk_add_f32 v[4:5], v[12:13], 1.0 op_sel_hi:[1,0]
	v_pk_mul_f32 v[2:3], v[6:7], v[2:3]
	v_rcp_f32_e32 v4, v4
	v_rcp_f32_e32 v5, v5
	v_pk_mul_f32 v[6:7], v[16:17], v[10:11] op_sel_hi:[0,1]
	v_pk_mul_f32 v[0:1], v[0:1], v[6:7]
	s_andn2_b64 vcc, exec, s[8:9]
	v_cvt_pk_bf16_f32 v10, v0, v1
	v_pk_mul_f32 v[0:1], v[16:17], v[4:5] op_sel_hi:[0,1]
	v_pk_mul_f32 v[0:1], v[2:3], v[0:1]
	s_mov_b64 s[8:9], -1
	v_cvt_pk_bf16_f32 v11, v0, v1
	v_add_u32_e32 v0, 0xb0, v167
	v_mad_i64_i32 v[0:1], s[14:15], v0, s59, v[112:113]
	v_lshl_add_u64 v[0:1], v[0:1], 0, v[114:115]
	global_store_dwordx4 v[0:1], v[8:11], off sc0 nt
	s_cbranch_vccnz .LBB0_442
	s_andn2_b64 vcc, exec, s[0:1]
	s_cbranch_vccnz .LBB0_441
	s_barrier
	s_branch .LBB0_441
